# stack + first K-iteration behind a tile epilogue counts the epilogue stores into the phase-1/2 vmcnt (w_in 24, up 16)
# baseline (speedup 1.0000x reference)
.LBB1_224:
	s_add_u32 s60, s40, 0xfff80080
	s_addc_u32 s61, s41, -1
	s_add_i32 s78, 0, 0x10000
	s_cmp_eq_u32 s77, 28
	s_cselect_b32 s63, s27, s61
	s_cselect_b32 s62, s39, s60
	v_add_u32_e32 v112, s78, v148
	s_cselect_b32 s61, s72, s76
	s_cselect_b32 s60, s74, s75
	s_add_i32 s80, 0, 0x14000
	ds_read_b128 v[142:145], v112
	ds_read_b128 v[150:153], v112 offset:1024
	ds_read_b128 v[154:157], v112 offset:2048
	ds_read_b128 v[158:161], v112 offset:3072
	v_add_u32_e32 v112, s80, v148
	ds_read_b128 v[162:165], v112
	ds_read_b128 v[166:169], v112 offset:1024
	ds_read_b128 v[170:173], v112 offset:2048
	ds_read_b128 v[174:177], v112 offset:3072
	v_lshl_add_u64 v[146:147], s[40:41], 0, v[138:139]
	s_add_i32 m0, s9, 0xc000
	ds_read_b128 v[178:181], v149
	ds_read_b128 v[182:185], v149 offset:1024
	ds_read_b128 v[186:189], v149 offset:2048
	ds_read_b128 v[190:193], v149 offset:3072
	ds_read_b128 v[206:209], v149 offset:4096
	ds_read_b128 v[210:213], v149 offset:5120
	ds_read_b128 v[234:237], v149 offset:6144
	ds_read_b128 v[238:241], v149 offset:7168
	global_load_lds_dwordx4 v[146:147], off
	v_lshl_add_u64 v[146:147], s[40:41], 0, v[140:141]
	s_add_i32 m0, s9, 0xe000
	s_nop 0
	global_load_lds_dwordx4 v[146:147], off
	s_cmp_lg_u32 s77, -2
	s_cbranch_scc1 .Lrww1_n
	s_cmp_lt_u32 s66, 2
	s_cbranch_scc1 .Lrww1_n
	s_waitcnt vmcnt(24)
	s_branch .Lrww1_d
.Lrww1_n:
	s_waitcnt vmcnt(8)
.Lrww1_d:
	s_waitcnt lgkmcnt(0)
	s_barrier
	s_setprio 1
	s_waitcnt lgkmcnt(0)
	v_mfma_f32_16x16x32_bf16 v[126:129], v[142:145], v[178:181], v[126:129]
	v_mfma_f32_16x16x32_bf16 v[122:125], v[154:157], v[178:181], v[122:125]
	v_mfma_f32_16x16x32_bf16 v[108:111], v[142:145], v[186:189], v[108:111]
	v_mfma_f32_16x16x32_bf16 v[104:107], v[154:157], v[186:189], v[104:107]
	v_mfma_f32_16x16x32_bf16 v[92:95], v[142:145], v[206:209], v[92:95]
	v_mfma_f32_16x16x32_bf16 v[88:91], v[154:157], v[206:209], v[88:91]
	v_mfma_f32_16x16x32_bf16 v[76:79], v[142:145], v[234:237], v[76:79]
	v_mfma_f32_16x16x32_bf16 v[72:75], v[154:157], v[234:237], v[72:75]
	v_mfma_f32_16x16x32_bf16 v[126:129], v[150:153], v[182:185], v[126:129]
	v_mfma_f32_16x16x32_bf16 v[122:125], v[158:161], v[182:185], v[122:125]
	v_mfma_f32_16x16x32_bf16 v[108:111], v[150:153], v[190:193], v[108:111]
	v_mfma_f32_16x16x32_bf16 v[104:107], v[158:161], v[190:193], v[104:107]
	v_mfma_f32_16x16x32_bf16 v[92:95], v[150:153], v[210:213], v[92:95]
	v_mfma_f32_16x16x32_bf16 v[88:91], v[158:161], v[210:213], v[88:91]
	v_mfma_f32_16x16x32_bf16 v[76:79], v[150:153], v[238:241], v[76:79]
	v_mfma_f32_16x16x32_bf16 v[72:75], v[158:161], v[238:241], v[72:75]
	s_setprio 0
	s_setprio 1
	v_mfma_f32_16x16x32_bf16 v[118:121], v[162:165], v[178:181], v[118:121]
	v_mfma_f32_16x16x32_bf16 v[114:117], v[170:173], v[178:181], v[114:117]
	v_mfma_f32_16x16x32_bf16 v[100:103], v[162:165], v[186:189], v[100:103]
	v_mfma_f32_16x16x32_bf16 v[96:99], v[170:173], v[186:189], v[96:99]
	v_mfma_f32_16x16x32_bf16 v[84:87], v[162:165], v[206:209], v[84:87]
	v_mfma_f32_16x16x32_bf16 v[80:83], v[170:173], v[206:209], v[80:83]
	v_mfma_f32_16x16x32_bf16 v[68:71], v[162:165], v[234:237], v[68:71]
	v_mfma_f32_16x16x32_bf16 v[64:67], v[170:173], v[234:237], v[64:67]
	v_mfma_f32_16x16x32_bf16 v[118:121], v[166:169], v[182:185], v[118:121]
	v_mfma_f32_16x16x32_bf16 v[114:117], v[174:177], v[182:185], v[114:117]
	v_mfma_f32_16x16x32_bf16 v[100:103], v[166:169], v[190:193], v[100:103]
	v_mfma_f32_16x16x32_bf16 v[96:99], v[174:177], v[190:193], v[96:99]
	v_mfma_f32_16x16x32_bf16 v[84:87], v[166:169], v[210:213], v[84:87]
	v_mfma_f32_16x16x32_bf16 v[80:83], v[174:177], v[210:213], v[80:83]
	v_mfma_f32_16x16x32_bf16 v[68:71], v[166:169], v[238:241], v[68:71]
	v_mfma_f32_16x16x32_bf16 v[64:67], v[174:177], v[238:241], v[64:67]
	s_setprio 0
	s_barrier
	s_add_i32 s78, s78, s7
	v_lshl_add_u64 v[146:147], s[60:61], 0, v[132:133]
	s_mov_b32 m0, s78
	ds_read_b128 v[178:181], v149 offset:16384
	ds_read_b128 v[182:185], v149 offset:17408
	ds_read_b128 v[186:189], v149 offset:18432
	ds_read_b128 v[190:193], v149 offset:19456
	ds_read_b128 v[206:209], v149 offset:20480
	ds_read_b128 v[210:213], v149 offset:21504
	ds_read_b128 v[234:237], v149 offset:22528
	ds_read_b128 v[238:241], v149 offset:23552
	global_load_lds_dwordx4 v[146:147], off
	s_add_i32 m0, s78, 0x2000
	s_add_u32 s78, s60, 0x20000
	v_lshl_add_u64 v[198:199], s[60:61], 0, v[136:137]
	s_addc_u32 s79, s61, 0
	s_add_i32 s80, s80, s7
	global_load_lds_dwordx4 v[198:199], off
	v_lshl_add_u64 v[200:201], s[78:79], 0, v[132:133]
	s_mov_b32 m0, s80
	v_lshl_add_u64 v[242:243], s[62:63], 0, v[134:135]
	global_load_lds_dwordx4 v[200:201], off
	v_lshl_add_u64 v[200:201], s[78:79], 0, v[136:137]
	s_add_i32 m0, s80, 0x2000
	s_nop 0
	global_load_lds_dwordx4 v[200:201], off
	v_lshl_add_u64 v[200:201], s[62:63], 0, v[130:131]
	s_mov_b32 m0, s9
	s_nop 0
	global_load_lds_dwordx4 v[200:201], off
	s_mov_b32 m0, s10
	s_nop 0
	global_load_lds_dwordx4 v[242:243], off
	s_cmp_lg_u32 s77, -2
	s_cbranch_scc1 .Lrww2_n
	s_cmp_lt_u32 s66, 2
	s_cbranch_scc1 .Lrww2_n
	s_waitcnt vmcnt(24)
	s_branch .Lrww2_d

.Lrww2_d:
	s_waitcnt lgkmcnt(0)
	s_barrier
	s_setprio 1
	s_waitcnt lgkmcnt(0)
	v_mfma_f32_16x16x32_bf16 v[60:63], v[142:145], v[178:181], v[60:63]
	v_mfma_f32_16x16x32_bf16 v[56:59], v[154:157], v[178:181], v[56:59]
	v_mfma_f32_16x16x32_bf16 v[44:47], v[142:145], v[186:189], v[44:47]
	v_mfma_f32_16x16x32_bf16 v[40:43], v[154:157], v[186:189], v[40:43]
	v_mfma_f32_16x16x32_bf16 v[28:31], v[142:145], v[206:209], v[28:31]
	v_mfma_f32_16x16x32_bf16 v[24:27], v[154:157], v[206:209], v[24:27]
	v_mfma_f32_16x16x32_bf16 v[12:15], v[142:145], v[234:237], v[12:15]
	v_mfma_f32_16x16x32_bf16 v[8:11], v[154:157], v[234:237], v[8:11]
	v_mfma_f32_16x16x32_bf16 v[60:63], v[150:153], v[182:185], v[60:63]
	v_mfma_f32_16x16x32_bf16 v[56:59], v[158:161], v[182:185], v[56:59]
	v_mfma_f32_16x16x32_bf16 v[44:47], v[150:153], v[190:193], v[44:47]
	v_mfma_f32_16x16x32_bf16 v[40:43], v[158:161], v[190:193], v[40:43]
	v_mfma_f32_16x16x32_bf16 v[28:31], v[150:153], v[210:213], v[28:31]
	v_mfma_f32_16x16x32_bf16 v[24:27], v[158:161], v[210:213], v[24:27]
	v_mfma_f32_16x16x32_bf16 v[12:15], v[150:153], v[238:241], v[12:15]
	v_mfma_f32_16x16x32_bf16 v[8:11], v[158:161], v[238:241], v[8:11]
	s_setprio 0
	s_setprio 1
	v_mfma_f32_16x16x32_bf16 v[52:55], v[162:165], v[178:181], v[52:55]
	v_mfma_f32_16x16x32_bf16 v[48:51], v[170:173], v[178:181], v[48:51]
	v_mfma_f32_16x16x32_bf16 v[36:39], v[162:165], v[186:189], v[36:39]
	v_mfma_f32_16x16x32_bf16 v[32:35], v[170:173], v[186:189], v[32:35]
	v_mfma_f32_16x16x32_bf16 v[20:23], v[162:165], v[206:209], v[20:23]
	v_mfma_f32_16x16x32_bf16 v[16:19], v[170:173], v[206:209], v[16:19]
	v_mfma_f32_16x16x32_bf16 v[4:7], v[162:165], v[234:237], v[4:7]
	v_mfma_f32_16x16x32_bf16 v[0:3], v[170:173], v[234:237], v[0:3]
	v_mfma_f32_16x16x32_bf16 v[52:55], v[166:169], v[182:185], v[52:55]
	v_mfma_f32_16x16x32_bf16 v[48:51], v[174:177], v[182:185], v[48:51]
	v_mfma_f32_16x16x32_bf16 v[36:39], v[166:169], v[190:193], v[36:39]
	v_mfma_f32_16x16x32_bf16 v[32:35], v[174:177], v[190:193], v[32:35]
	v_mfma_f32_16x16x32_bf16 v[20:23], v[166:169], v[210:213], v[20:23]
	v_mfma_f32_16x16x32_bf16 v[16:19], v[174:177], v[210:213], v[16:19]
	v_mfma_f32_16x16x32_bf16 v[4:7], v[166:169], v[238:241], v[4:7]
	v_mfma_f32_16x16x32_bf16 v[0:3], v[174:177], v[238:241], v[0:3]
	s_setprio 0
	s_barrier
	s_add_i32 s78, 0, 0x18000
	v_add_u32_e32 v112, s78, v148
	s_add_i32 s79, 0, 0x1c000
	ds_read_b128 v[142:145], v112
	ds_read_b128 v[150:153], v112 offset:1024
	ds_read_b128 v[154:157], v112 offset:2048
	ds_read_b128 v[158:161], v112 offset:3072
	v_add_u32_e32 v112, s79, v148
	ds_read_b128 v[162:165], v112
	ds_read_b128 v[166:169], v112 offset:1024
	ds_read_b128 v[170:173], v112 offset:2048
	ds_read_b128 v[174:177], v112 offset:3072
	s_add_u32 s62, s62, 0x80000
	s_addc_u32 s63, s63, 0
	s_mov_b32 m0, s11
	v_lshl_add_u64 v[244:245], s[62:63], 0, v[130:131]
	ds_read_b128 v[178:181], v149 offset:32768
	ds_read_b128 v[182:185], v149 offset:33792
	ds_read_b128 v[186:189], v149 offset:34816
	ds_read_b128 v[190:193], v149 offset:35840
	ds_read_b128 v[206:209], v149 offset:36864
	ds_read_b128 v[210:213], v149 offset:37888
	ds_read_b128 v[234:237], v149 offset:38912
	ds_read_b128 v[238:241], v149 offset:39936
	global_load_lds_dwordx4 v[244:245], off
	v_lshl_add_u64 v[244:245], s[62:63], 0, v[134:135]
	s_mov_b32 m0, s24
	s_nop 0
	global_load_lds_dwordx4 v[244:245], off
	s_waitcnt vmcnt(8)
	s_waitcnt lgkmcnt(0)
	s_barrier
	s_setprio 1
	s_waitcnt lgkmcnt(0)
	v_mfma_f32_16x16x32_bf16 v[126:129], v[142:145], v[178:181], v[126:129]
	v_mfma_f32_16x16x32_bf16 v[122:125], v[154:157], v[178:181], v[122:125]
	v_mfma_f32_16x16x32_bf16 v[108:111], v[142:145], v[186:189], v[108:111]
	v_mfma_f32_16x16x32_bf16 v[104:107], v[154:157], v[186:189], v[104:107]
	v_mfma_f32_16x16x32_bf16 v[92:95], v[142:145], v[206:209], v[92:95]
	v_mfma_f32_16x16x32_bf16 v[88:91], v[154:157], v[206:209], v[88:91]
	v_mfma_f32_16x16x32_bf16 v[76:79], v[142:145], v[234:237], v[76:79]
	v_mfma_f32_16x16x32_bf16 v[72:75], v[154:157], v[234:237], v[72:75]
	v_mfma_f32_16x16x32_bf16 v[126:129], v[150:153], v[182:185], v[126:129]
	v_mfma_f32_16x16x32_bf16 v[122:125], v[158:161], v[182:185], v[122:125]
	v_mfma_f32_16x16x32_bf16 v[108:111], v[150:153], v[190:193], v[108:111]
	v_mfma_f32_16x16x32_bf16 v[104:107], v[158:161], v[190:193], v[104:107]
	v_mfma_f32_16x16x32_bf16 v[92:95], v[150:153], v[210:213], v[92:95]
	v_mfma_f32_16x16x32_bf16 v[88:91], v[158:161], v[210:213], v[88:91]
	v_mfma_f32_16x16x32_bf16 v[76:79], v[150:153], v[238:241], v[76:79]
	v_mfma_f32_16x16x32_bf16 v[72:75], v[158:161], v[238:241], v[72:75]
	s_setprio 0
	s_setprio 1
	v_mfma_f32_16x16x32_bf16 v[118:121], v[162:165], v[178:181], v[118:121]
	v_mfma_f32_16x16x32_bf16 v[114:117], v[170:173], v[178:181], v[114:117]
	v_mfma_f32_16x16x32_bf16 v[100:103], v[162:165], v[186:189], v[100:103]
	v_mfma_f32_16x16x32_bf16 v[96:99], v[170:173], v[186:189], v[96:99]
	v_mfma_f32_16x16x32_bf16 v[84:87], v[162:165], v[206:209], v[84:87]
	v_mfma_f32_16x16x32_bf16 v[80:83], v[170:173], v[206:209], v[80:83]
	v_mfma_f32_16x16x32_bf16 v[68:71], v[162:165], v[234:237], v[68:71]
	v_mfma_f32_16x16x32_bf16 v[64:67], v[170:173], v[234:237], v[64:67]
	v_mfma_f32_16x16x32_bf16 v[118:121], v[166:169], v[182:185], v[118:121]
	v_mfma_f32_16x16x32_bf16 v[114:117], v[174:177], v[182:185], v[114:117]
	v_mfma_f32_16x16x32_bf16 v[100:103], v[166:169], v[190:193], v[100:103]
	v_mfma_f32_16x16x32_bf16 v[96:99], v[174:177], v[190:193], v[96:99]
	v_mfma_f32_16x16x32_bf16 v[84:87], v[166:169], v[210:213], v[84:87]
	v_mfma_f32_16x16x32_bf16 v[80:83], v[174:177], v[210:213], v[80:83]
	v_mfma_f32_16x16x32_bf16 v[68:71], v[166:169], v[238:241], v[68:71]
	v_mfma_f32_16x16x32_bf16 v[64:67], v[174:177], v[238:241], v[64:67]
	s_setprio 0
	s_barrier
	s_add_i32 s62, s78, s7
	v_lshl_add_u64 v[146:147], v[146:147], 0, s[48:49]
	s_mov_b32 m0, s62
	ds_read_b128 v[178:181], v149 offset:49152
	ds_read_b128 v[182:185], v149 offset:50176
	ds_read_b128 v[186:189], v149 offset:51200
	ds_read_b128 v[190:193], v149 offset:52224
	ds_read_b128 v[206:209], v149 offset:53248
	ds_read_b128 v[210:213], v149 offset:54272
	ds_read_b128 v[234:237], v149 offset:55296
	ds_read_b128 v[238:241], v149 offset:56320
	global_load_lds_dwordx4 v[146:147], off
	s_add_i32 m0, s62, 0x2000
	s_add_u32 s60, s60, 0x20080
	v_lshl_add_u64 v[146:147], v[198:199], 0, s[48:49]
	s_addc_u32 s61, s61, 0
	s_add_i32 s62, s79, s7
	global_load_lds_dwordx4 v[146:147], off
	v_lshl_add_u64 v[146:147], s[60:61], 0, v[132:133]
	s_mov_b32 m0, s62
	s_nop 0
	global_load_lds_dwordx4 v[146:147], off
	v_lshl_add_u64 v[146:147], s[60:61], 0, v[136:137]
	s_add_i32 m0, s62, 0x2000
	s_nop 0
	global_load_lds_dwordx4 v[146:147], off
	v_lshl_add_u64 v[146:147], v[200:201], 0, s[48:49]
	s_mov_b32 m0, s54
	s_nop 0
	global_load_lds_dwordx4 v[146:147], off
	v_lshl_add_u64 v[146:147], v[242:243], 0, s[48:49]
	s_mov_b32 m0, s55
	s_nop 0
	global_load_lds_dwordx4 v[146:147], off
	s_waitcnt vmcnt(8)
	s_waitcnt lgkmcnt(0)
	s_barrier
	s_setprio 1
	s_waitcnt lgkmcnt(0)
	v_mfma_f32_16x16x32_bf16 v[60:63], v[142:145], v[178:181], v[60:63]
	v_mfma_f32_16x16x32_bf16 v[56:59], v[154:157], v[178:181], v[56:59]
	v_mfma_f32_16x16x32_bf16 v[44:47], v[142:145], v[186:189], v[44:47]
	v_mfma_f32_16x16x32_bf16 v[40:43], v[154:157], v[186:189], v[40:43]
	v_mfma_f32_16x16x32_bf16 v[28:31], v[142:145], v[206:209], v[28:31]
	v_mfma_f32_16x16x32_bf16 v[24:27], v[154:157], v[206:209], v[24:27]
	v_mfma_f32_16x16x32_bf16 v[12:15], v[142:145], v[234:237], v[12:15]
	v_mfma_f32_16x16x32_bf16 v[8:11], v[154:157], v[234:237], v[8:11]
	v_mfma_f32_16x16x32_bf16 v[60:63], v[150:153], v[182:185], v[60:63]
	v_mfma_f32_16x16x32_bf16 v[56:59], v[158:161], v[182:185], v[56:59]
	v_mfma_f32_16x16x32_bf16 v[44:47], v[150:153], v[190:193], v[44:47]
	v_mfma_f32_16x16x32_bf16 v[40:43], v[158:161], v[190:193], v[40:43]
	v_mfma_f32_16x16x32_bf16 v[28:31], v[150:153], v[210:213], v[28:31]
	v_mfma_f32_16x16x32_bf16 v[24:27], v[158:161], v[210:213], v[24:27]
	v_mfma_f32_16x16x32_bf16 v[12:15], v[150:153], v[238:241], v[12:15]
	v_mfma_f32_16x16x32_bf16 v[8:11], v[158:161], v[238:241], v[8:11]
	s_setprio 0
	s_setprio 1
	v_mfma_f32_16x16x32_bf16 v[52:55], v[162:165], v[178:181], v[52:55]
	v_mfma_f32_16x16x32_bf16 v[48:51], v[170:173], v[178:181], v[48:51]
	v_mfma_f32_16x16x32_bf16 v[36:39], v[162:165], v[186:189], v[36:39]
	v_mfma_f32_16x16x32_bf16 v[32:35], v[170:173], v[186:189], v[32:35]
	v_mfma_f32_16x16x32_bf16 v[20:23], v[162:165], v[206:209], v[20:23]
	v_mfma_f32_16x16x32_bf16 v[16:19], v[170:173], v[206:209], v[16:19]
	v_mfma_f32_16x16x32_bf16 v[4:7], v[162:165], v[234:237], v[4:7]
	v_mfma_f32_16x16x32_bf16 v[0:3], v[170:173], v[234:237], v[0:3]
	v_mfma_f32_16x16x32_bf16 v[52:55], v[166:169], v[182:185], v[52:55]
	v_mfma_f32_16x16x32_bf16 v[48:51], v[174:177], v[182:185], v[48:51]
	v_mfma_f32_16x16x32_bf16 v[36:39], v[166:169], v[190:193], v[36:39]
	v_mfma_f32_16x16x32_bf16 v[32:35], v[174:177], v[190:193], v[32:35]
	v_mfma_f32_16x16x32_bf16 v[20:23], v[166:169], v[210:213], v[20:23]
	v_mfma_f32_16x16x32_bf16 v[16:19], v[174:177], v[210:213], v[16:19]
	v_mfma_f32_16x16x32_bf16 v[4:7], v[166:169], v[238:241], v[4:7]
	v_mfma_f32_16x16x32_bf16 v[0:3], v[174:177], v[238:241], v[0:3]
	s_setprio 0
	s_barrier
	s_add_i32 s77, s77, 2
	s_add_u32 s40, s40, 0x100
	s_addc_u32 s41, s41, 0
	s_add_u32 s75, s75, 0x100
	s_addc_u32 s76, s76, 0
	s_cmp_gt_u32 s77, 29
	s_cbranch_scc0 .LBB1_224
	s_and_b64 vcc, exec, s[18:19]
	s_cbranch_vccz .LBB1_227
	s_barrier

.LBB1_939:
	s_add_u32 s38, s26, 0xfff80080
	s_addc_u32 s39, s27, -1
	s_add_i32 s94, 0, 0x10000
	s_cmp_eq_u32 vcc_lo, 28
	s_cselect_b32 s41, s19, s39
	s_cselect_b32 s40, s31, s38
	v_add_u32_e32 v112, s94, v166
	s_cselect_b32 s39, s42, s45
	s_cselect_b32 s38, s43, s44
	s_add_i32 vcc_hi, 0, 0x14000
	ds_read_b128 v[130:133], v112
	ds_read_b128 v[134:137], v112 offset:1024
	ds_read_b128 v[138:141], v112 offset:2048
	ds_read_b128 v[142:145], v112 offset:3072
	v_add_u32_e32 v112, vcc_hi, v166
	ds_read_b128 v[146:149], v112
	ds_read_b128 v[150:153], v112 offset:1024
	ds_read_b128 v[168:171], v112 offset:2048
	ds_read_b128 v[172:175], v112 offset:3072
	v_lshl_add_u64 v[192:193], s[26:27], 0, v[162:163]
	s_add_i32 m0, s7, 0xc000
	ds_read_b128 v[176:179], v167
	ds_read_b128 v[180:183], v167 offset:1024
	ds_read_b128 v[184:187], v167 offset:2048
	ds_read_b128 v[188:191], v167 offset:3072
	ds_read_b128 v[198:201], v167 offset:4096
	ds_read_b128 v[206:209], v167 offset:5120
	ds_read_b128 v[210:213], v167 offset:6144
	ds_read_b128 v[234:237], v167 offset:7168
	global_load_lds_dwordx4 v[192:193], off
	v_lshl_add_u64 v[192:193], s[26:27], 0, v[164:165]
	s_add_i32 m0, s7, 0xe000
	s_nop 0
	global_load_lds_dwordx4 v[192:193], off
	s_cmp_lg_u32 vcc_lo, -2
	s_cbranch_scc1 .Lrwu1_n
	s_cmp_lt_u32 s55, 2
	s_cbranch_scc1 .Lrwu1_n
	s_waitcnt vmcnt(16)
	s_branch .Lrwu1_d

.Lrwu1_d:
	s_waitcnt lgkmcnt(0)
	s_barrier
	s_setprio 1
	s_waitcnt lgkmcnt(0)
	v_mfma_f32_16x16x32_bf16 v[108:111], v[130:133], v[176:179], v[108:111]
	v_mfma_f32_16x16x32_bf16 v[84:87], v[138:141], v[176:179], v[84:87]
	v_mfma_f32_16x16x32_bf16 v[126:129], v[130:133], v[184:187], v[126:129]
	v_mfma_f32_16x16x32_bf16 v[92:95], v[138:141], v[184:187], v[92:95]
	v_mfma_f32_16x16x32_bf16 v[122:125], v[130:133], v[198:201], v[122:125]
	v_mfma_f32_16x16x32_bf16 v[88:91], v[138:141], v[198:201], v[88:91]
	v_mfma_f32_16x16x32_bf16 v[104:107], v[130:133], v[210:213], v[104:107]
	v_mfma_f32_16x16x32_bf16 v[76:79], v[138:141], v[210:213], v[76:79]
	v_mfma_f32_16x16x32_bf16 v[108:111], v[134:137], v[180:183], v[108:111]
	v_mfma_f32_16x16x32_bf16 v[84:87], v[142:145], v[180:183], v[84:87]
	v_mfma_f32_16x16x32_bf16 v[126:129], v[134:137], v[188:191], v[126:129]
	v_mfma_f32_16x16x32_bf16 v[92:95], v[142:145], v[188:191], v[92:95]
	v_mfma_f32_16x16x32_bf16 v[122:125], v[134:137], v[206:209], v[122:125]
	v_mfma_f32_16x16x32_bf16 v[88:91], v[142:145], v[206:209], v[88:91]
	v_mfma_f32_16x16x32_bf16 v[104:107], v[134:137], v[234:237], v[104:107]
	v_mfma_f32_16x16x32_bf16 v[76:79], v[142:145], v[234:237], v[76:79]
	s_setprio 0
	s_setprio 1
	v_mfma_f32_16x16x32_bf16 v[100:103], v[146:149], v[176:179], v[100:103]
	v_mfma_f32_16x16x32_bf16 v[68:71], v[168:171], v[176:179], v[68:71]
	v_mfma_f32_16x16x32_bf16 v[118:121], v[146:149], v[184:187], v[118:121]
	v_mfma_f32_16x16x32_bf16 v[80:83], v[168:171], v[184:187], v[80:83]
	v_mfma_f32_16x16x32_bf16 v[114:117], v[146:149], v[198:201], v[114:117]
	v_mfma_f32_16x16x32_bf16 v[72:75], v[168:171], v[198:201], v[72:75]
	v_mfma_f32_16x16x32_bf16 v[96:99], v[146:149], v[210:213], v[96:99]
	v_mfma_f32_16x16x32_bf16 v[64:67], v[168:171], v[210:213], v[64:67]
	v_mfma_f32_16x16x32_bf16 v[100:103], v[150:153], v[180:183], v[100:103]
	v_mfma_f32_16x16x32_bf16 v[68:71], v[172:175], v[180:183], v[68:71]
	v_mfma_f32_16x16x32_bf16 v[118:121], v[150:153], v[188:191], v[118:121]
	v_mfma_f32_16x16x32_bf16 v[80:83], v[172:175], v[188:191], v[80:83]
	v_mfma_f32_16x16x32_bf16 v[114:117], v[150:153], v[206:209], v[114:117]
	v_mfma_f32_16x16x32_bf16 v[72:75], v[172:175], v[206:209], v[72:75]
	v_mfma_f32_16x16x32_bf16 v[96:99], v[150:153], v[234:237], v[96:99]
	v_mfma_f32_16x16x32_bf16 v[64:67], v[172:175], v[234:237], v[64:67]
	s_setprio 0
	s_barrier
	s_add_i32 s94, s94, s6
	v_lshl_add_u64 v[192:193], s[38:39], 0, v[156:157]
	s_mov_b32 m0, s94
	ds_read_b128 v[176:179], v167 offset:16384
	ds_read_b128 v[180:183], v167 offset:17408
	ds_read_b128 v[184:187], v167 offset:18432
	ds_read_b128 v[188:191], v167 offset:19456
	ds_read_b128 v[198:201], v167 offset:20480
	ds_read_b128 v[206:209], v167 offset:21504
	ds_read_b128 v[210:213], v167 offset:22528
	ds_read_b128 v[234:237], v167 offset:23552
	global_load_lds_dwordx4 v[192:193], off
	s_add_i32 m0, s94, 0x2000
	s_add_u32 s94, s38, 0x20000
	v_lshl_add_u64 v[238:239], s[38:39], 0, v[160:161]
	s_addc_u32 s95, s39, 0
	s_add_i32 vcc_hi, vcc_hi, s6
	global_load_lds_dwordx4 v[238:239], off
	v_lshl_add_u64 v[240:241], s[94:95], 0, v[156:157]
	s_mov_b32 m0, vcc_hi
	v_lshl_add_u64 v[242:243], s[40:41], 0, v[158:159]
	global_load_lds_dwordx4 v[240:241], off
	v_lshl_add_u64 v[240:241], s[94:95], 0, v[160:161]
	s_add_i32 m0, vcc_hi, 0x2000
	s_nop 0
	global_load_lds_dwordx4 v[240:241], off
	v_lshl_add_u64 v[240:241], s[40:41], 0, v[154:155]
	s_mov_b32 m0, s7
	s_nop 0
	global_load_lds_dwordx4 v[240:241], off
	s_mov_b32 m0, s2
	s_nop 0
	global_load_lds_dwordx4 v[242:243], off
	s_cmp_lg_u32 vcc_lo, -2
	s_cbranch_scc1 .Lrwu2_n
	s_cmp_lt_u32 s55, 2
	s_cbranch_scc1 .Lrwu2_n
	s_waitcnt vmcnt(16)
	s_branch .Lrwu2_d

.Lrwu2_d:
	s_waitcnt lgkmcnt(0)
	s_barrier
	s_setprio 1
	s_waitcnt lgkmcnt(0)
	v_mfma_f32_16x16x32_bf16 v[52:55], v[130:133], v[176:179], v[52:55]
	v_mfma_f32_16x16x32_bf16 v[20:23], v[138:141], v[176:179], v[20:23]
	v_mfma_f32_16x16x32_bf16 v[60:63], v[130:133], v[184:187], v[60:63]
	v_mfma_f32_16x16x32_bf16 v[28:31], v[138:141], v[184:187], v[28:31]
	v_mfma_f32_16x16x32_bf16 v[56:59], v[130:133], v[198:201], v[56:59]
	v_mfma_f32_16x16x32_bf16 v[24:27], v[138:141], v[198:201], v[24:27]
	v_mfma_f32_16x16x32_bf16 v[48:51], v[130:133], v[210:213], v[48:51]
	v_mfma_f32_16x16x32_bf16 v[16:19], v[138:141], v[210:213], v[16:19]
	v_mfma_f32_16x16x32_bf16 v[52:55], v[134:137], v[180:183], v[52:55]
	v_mfma_f32_16x16x32_bf16 v[20:23], v[142:145], v[180:183], v[20:23]
	v_mfma_f32_16x16x32_bf16 v[60:63], v[134:137], v[188:191], v[60:63]
	v_mfma_f32_16x16x32_bf16 v[28:31], v[142:145], v[188:191], v[28:31]
	v_mfma_f32_16x16x32_bf16 v[56:59], v[134:137], v[206:209], v[56:59]
	v_mfma_f32_16x16x32_bf16 v[24:27], v[142:145], v[206:209], v[24:27]
	v_mfma_f32_16x16x32_bf16 v[48:51], v[134:137], v[234:237], v[48:51]
	v_mfma_f32_16x16x32_bf16 v[16:19], v[142:145], v[234:237], v[16:19]
	s_setprio 0
	s_setprio 1
	v_mfma_f32_16x16x32_bf16 v[36:39], v[146:149], v[176:179], v[36:39]
	v_mfma_f32_16x16x32_bf16 v[4:7], v[168:171], v[176:179], v[4:7]
	v_mfma_f32_16x16x32_bf16 v[44:47], v[146:149], v[184:187], v[44:47]
	v_mfma_f32_16x16x32_bf16 v[12:15], v[168:171], v[184:187], v[12:15]
	v_mfma_f32_16x16x32_bf16 v[40:43], v[146:149], v[198:201], v[40:43]
	v_mfma_f32_16x16x32_bf16 v[8:11], v[168:171], v[198:201], v[8:11]
	v_mfma_f32_16x16x32_bf16 v[32:35], v[146:149], v[210:213], v[32:35]
	v_mfma_f32_16x16x32_bf16 v[0:3], v[168:171], v[210:213], v[0:3]
	v_mfma_f32_16x16x32_bf16 v[36:39], v[150:153], v[180:183], v[36:39]
	v_mfma_f32_16x16x32_bf16 v[4:7], v[172:175], v[180:183], v[4:7]
	v_mfma_f32_16x16x32_bf16 v[44:47], v[150:153], v[188:191], v[44:47]
	v_mfma_f32_16x16x32_bf16 v[12:15], v[172:175], v[188:191], v[12:15]
	v_mfma_f32_16x16x32_bf16 v[40:43], v[150:153], v[206:209], v[40:43]
	v_mfma_f32_16x16x32_bf16 v[8:11], v[172:175], v[206:209], v[8:11]
	v_mfma_f32_16x16x32_bf16 v[32:35], v[150:153], v[234:237], v[32:35]
	v_mfma_f32_16x16x32_bf16 v[0:3], v[172:175], v[234:237], v[0:3]
	s_setprio 0
	s_barrier
	s_add_i32 s94, 0, 0x18000
	v_add_u32_e32 v112, s94, v166
	s_add_i32 s95, 0, 0x1c000
	ds_read_b128 v[130:133], v112
	ds_read_b128 v[134:137], v112 offset:1024
	ds_read_b128 v[138:141], v112 offset:2048
	ds_read_b128 v[142:145], v112 offset:3072
	v_add_u32_e32 v112, s95, v166
	ds_read_b128 v[146:149], v112
	ds_read_b128 v[150:153], v112 offset:1024
	ds_read_b128 v[168:171], v112 offset:2048
	ds_read_b128 v[172:175], v112 offset:3072
	s_add_u32 s40, s40, 0x80000
	s_addc_u32 s41, s41, 0
	s_mov_b32 m0, s3
	v_lshl_add_u64 v[244:245], s[40:41], 0, v[154:155]
	ds_read_b128 v[176:179], v167 offset:32768
	ds_read_b128 v[180:183], v167 offset:33792
	ds_read_b128 v[184:187], v167 offset:34816
	ds_read_b128 v[188:191], v167 offset:35840
	ds_read_b128 v[198:201], v167 offset:36864
	ds_read_b128 v[206:209], v167 offset:37888
	ds_read_b128 v[210:213], v167 offset:38912
	ds_read_b128 v[234:237], v167 offset:39936
	global_load_lds_dwordx4 v[244:245], off
	v_lshl_add_u64 v[244:245], s[40:41], 0, v[158:159]
	s_mov_b32 m0, s5
	s_nop 0
	global_load_lds_dwordx4 v[244:245], off
	s_waitcnt vmcnt(8)
	s_waitcnt lgkmcnt(0)
	s_barrier
	s_setprio 1
	s_waitcnt lgkmcnt(0)
	v_mfma_f32_16x16x32_bf16 v[108:111], v[130:133], v[176:179], v[108:111]
	v_mfma_f32_16x16x32_bf16 v[84:87], v[138:141], v[176:179], v[84:87]
	v_mfma_f32_16x16x32_bf16 v[126:129], v[130:133], v[184:187], v[126:129]
	v_mfma_f32_16x16x32_bf16 v[92:95], v[138:141], v[184:187], v[92:95]
	v_mfma_f32_16x16x32_bf16 v[122:125], v[130:133], v[198:201], v[122:125]
	v_mfma_f32_16x16x32_bf16 v[88:91], v[138:141], v[198:201], v[88:91]
	v_mfma_f32_16x16x32_bf16 v[104:107], v[130:133], v[210:213], v[104:107]
	v_mfma_f32_16x16x32_bf16 v[76:79], v[138:141], v[210:213], v[76:79]
	v_mfma_f32_16x16x32_bf16 v[108:111], v[134:137], v[180:183], v[108:111]
	v_mfma_f32_16x16x32_bf16 v[84:87], v[142:145], v[180:183], v[84:87]
	v_mfma_f32_16x16x32_bf16 v[126:129], v[134:137], v[188:191], v[126:129]
	v_mfma_f32_16x16x32_bf16 v[92:95], v[142:145], v[188:191], v[92:95]
	v_mfma_f32_16x16x32_bf16 v[122:125], v[134:137], v[206:209], v[122:125]
	v_mfma_f32_16x16x32_bf16 v[88:91], v[142:145], v[206:209], v[88:91]
	v_mfma_f32_16x16x32_bf16 v[104:107], v[134:137], v[234:237], v[104:107]
	v_mfma_f32_16x16x32_bf16 v[76:79], v[142:145], v[234:237], v[76:79]
	s_setprio 0
	s_setprio 1
	v_mfma_f32_16x16x32_bf16 v[100:103], v[146:149], v[176:179], v[100:103]
	v_mfma_f32_16x16x32_bf16 v[68:71], v[168:171], v[176:179], v[68:71]
	v_mfma_f32_16x16x32_bf16 v[118:121], v[146:149], v[184:187], v[118:121]
	v_mfma_f32_16x16x32_bf16 v[80:83], v[168:171], v[184:187], v[80:83]
	v_mfma_f32_16x16x32_bf16 v[114:117], v[146:149], v[198:201], v[114:117]
	v_mfma_f32_16x16x32_bf16 v[72:75], v[168:171], v[198:201], v[72:75]
	v_mfma_f32_16x16x32_bf16 v[96:99], v[146:149], v[210:213], v[96:99]
	v_mfma_f32_16x16x32_bf16 v[64:67], v[168:171], v[210:213], v[64:67]
	v_mfma_f32_16x16x32_bf16 v[100:103], v[150:153], v[180:183], v[100:103]
	v_mfma_f32_16x16x32_bf16 v[68:71], v[172:175], v[180:183], v[68:71]
	v_mfma_f32_16x16x32_bf16 v[118:121], v[150:153], v[188:191], v[118:121]
	v_mfma_f32_16x16x32_bf16 v[80:83], v[172:175], v[188:191], v[80:83]
	v_mfma_f32_16x16x32_bf16 v[114:117], v[150:153], v[206:209], v[114:117]
	v_mfma_f32_16x16x32_bf16 v[72:75], v[172:175], v[206:209], v[72:75]
	v_mfma_f32_16x16x32_bf16 v[96:99], v[150:153], v[234:237], v[96:99]
	v_mfma_f32_16x16x32_bf16 v[64:67], v[172:175], v[234:237], v[64:67]
	s_setprio 0
	s_barrier
	s_add_i32 s40, s94, s6
	v_lshl_add_u64 v[192:193], v[192:193], 0, s[48:49]
	s_mov_b32 m0, s40
	ds_read_b128 v[176:179], v167 offset:49152
	ds_read_b128 v[180:183], v167 offset:50176
	ds_read_b128 v[184:187], v167 offset:51200
	ds_read_b128 v[188:191], v167 offset:52224
	ds_read_b128 v[198:201], v167 offset:53248
	ds_read_b128 v[206:209], v167 offset:54272
	ds_read_b128 v[210:213], v167 offset:55296
	ds_read_b128 v[234:237], v167 offset:56320
	global_load_lds_dwordx4 v[192:193], off
	s_add_i32 m0, s40, 0x2000
	s_add_u32 s38, s38, 0x20080
	v_lshl_add_u64 v[192:193], v[238:239], 0, s[48:49]
	s_addc_u32 s39, s39, 0
	s_add_i32 s40, s95, s6
	global_load_lds_dwordx4 v[192:193], off
	v_lshl_add_u64 v[192:193], s[38:39], 0, v[156:157]
	s_mov_b32 m0, s40
	s_nop 0
	global_load_lds_dwordx4 v[192:193], off
	v_lshl_add_u64 v[192:193], s[38:39], 0, v[160:161]
	s_add_i32 m0, s40, 0x2000
	s_nop 0
	global_load_lds_dwordx4 v[192:193], off
	v_lshl_add_u64 v[192:193], v[240:241], 0, s[48:49]
	s_mov_b32 m0, s67
	s_nop 0
	global_load_lds_dwordx4 v[192:193], off
	v_lshl_add_u64 v[192:193], v[242:243], 0, s[48:49]
	s_mov_b32 m0, s9
	s_nop 0
	global_load_lds_dwordx4 v[192:193], off
	s_waitcnt vmcnt(8)
	s_waitcnt lgkmcnt(0)
	s_barrier
	s_setprio 1
	s_waitcnt lgkmcnt(0)
	v_mfma_f32_16x16x32_bf16 v[52:55], v[130:133], v[176:179], v[52:55]
	v_mfma_f32_16x16x32_bf16 v[20:23], v[138:141], v[176:179], v[20:23]
	v_mfma_f32_16x16x32_bf16 v[60:63], v[130:133], v[184:187], v[60:63]
	v_mfma_f32_16x16x32_bf16 v[28:31], v[138:141], v[184:187], v[28:31]
	v_mfma_f32_16x16x32_bf16 v[56:59], v[130:133], v[198:201], v[56:59]
	v_mfma_f32_16x16x32_bf16 v[24:27], v[138:141], v[198:201], v[24:27]
	v_mfma_f32_16x16x32_bf16 v[48:51], v[130:133], v[210:213], v[48:51]
	v_mfma_f32_16x16x32_bf16 v[16:19], v[138:141], v[210:213], v[16:19]
	v_mfma_f32_16x16x32_bf16 v[52:55], v[134:137], v[180:183], v[52:55]
	v_mfma_f32_16x16x32_bf16 v[20:23], v[142:145], v[180:183], v[20:23]
	v_mfma_f32_16x16x32_bf16 v[60:63], v[134:137], v[188:191], v[60:63]
	v_mfma_f32_16x16x32_bf16 v[28:31], v[142:145], v[188:191], v[28:31]
	v_mfma_f32_16x16x32_bf16 v[56:59], v[134:137], v[206:209], v[56:59]
	v_mfma_f32_16x16x32_bf16 v[24:27], v[142:145], v[206:209], v[24:27]
	v_mfma_f32_16x16x32_bf16 v[48:51], v[134:137], v[234:237], v[48:51]
	v_mfma_f32_16x16x32_bf16 v[16:19], v[142:145], v[234:237], v[16:19]
	s_setprio 0
	s_setprio 1
	v_mfma_f32_16x16x32_bf16 v[36:39], v[146:149], v[176:179], v[36:39]
	v_mfma_f32_16x16x32_bf16 v[4:7], v[168:171], v[176:179], v[4:7]
	v_mfma_f32_16x16x32_bf16 v[44:47], v[146:149], v[184:187], v[44:47]
	v_mfma_f32_16x16x32_bf16 v[12:15], v[168:171], v[184:187], v[12:15]
	v_mfma_f32_16x16x32_bf16 v[40:43], v[146:149], v[198:201], v[40:43]
	v_mfma_f32_16x16x32_bf16 v[8:11], v[168:171], v[198:201], v[8:11]
	v_mfma_f32_16x16x32_bf16 v[32:35], v[146:149], v[210:213], v[32:35]
	v_mfma_f32_16x16x32_bf16 v[0:3], v[168:171], v[210:213], v[0:3]
	v_mfma_f32_16x16x32_bf16 v[36:39], v[150:153], v[180:183], v[36:39]
	v_mfma_f32_16x16x32_bf16 v[4:7], v[172:175], v[180:183], v[4:7]
	v_mfma_f32_16x16x32_bf16 v[44:47], v[150:153], v[188:191], v[44:47]
	v_mfma_f32_16x16x32_bf16 v[12:15], v[172:175], v[188:191], v[12:15]
	v_mfma_f32_16x16x32_bf16 v[40:43], v[150:153], v[206:209], v[40:43]
	v_mfma_f32_16x16x32_bf16 v[8:11], v[172:175], v[206:209], v[8:11]
	v_mfma_f32_16x16x32_bf16 v[32:35], v[150:153], v[234:237], v[32:35]
	v_mfma_f32_16x16x32_bf16 v[0:3], v[172:175], v[234:237], v[0:3]
	s_setprio 0
	s_barrier
	s_add_i32 vcc_lo, vcc_lo, 2
	s_add_u32 s26, s26, 0x100
	s_addc_u32 s27, s27, 0
	s_add_u32 s44, s44, 0x100
	s_addc_u32 s45, s45, 0
	s_cmp_gt_u32 vcc_lo, 29
	s_cbranch_scc0 .LBB1_939
	s_and_b64 vcc, exec, s[80:81]
	s_cbranch_vccz .LBB1_942
	s_barrier
